# P1 SwiGLU epilogue hand-rewritten: row sums prefetched, no per-group vmcnt(0), 8 interleaved chains
# speedup vs baseline: 1.0030x; 1.0030x over previous
.LBB0_156:
	s_or_b64 exec, exec, s[0:1]
	s_add_u32 s16, s78, 0xaa00000
	s_addc_u32 s17, s79, 0
	s_add_u32 s18, s78, 0x8a00000
	s_addc_u32 s19, s79, 0
	s_cmpk_lt_i32 s95, 0x580
	s_cselect_b64 s[2:3], -1, 0
	v_writelane_b32 v254, s2, 54
	v_readlane_b32 s0, v253, 3
	v_readlane_b32 s1, v253, 4
	v_writelane_b32 v254, s3, 55
	v_mov_b32_e32 v14, v252
	v_writelane_b32 v254, s86, 56
	s_waitcnt lgkmcnt(0)
	s_barrier
	s_ashr_i32 s34, s0, 31
	s_ashr_i32 s80, s95, 31
	s_and_b64 vcc, exec, s[2:3]
	v_readfirstlane_b32 s1, v14
	v_writelane_b32 v254, s87, 57
	s_cbranch_vccz .LBB0_172
	v_lshlrev_b32_e32 v0, 4, v14
	v_add_u32_e32 v1, 0x2000, v0
	v_ashrrev_i32_e32 v2, 31, v1
	v_lshrrev_b32_e32 v2, 22, v2
	v_add_u32_e32 v2, v1, v2
	v_ashrrev_i32_e32 v8, 10, v2
	v_mul_i32_i24_e32 v2, 0x400, v8
	v_sub_u32_e32 v1, v1, v2
	v_lshrrev_b32_e32 v2, 4, v1
	v_bitop3_b32 v1, v2, v1, 32 bitop3:0x6c
	v_ashrrev_i32_e32 v2, 31, v1
	v_lshrrev_b32_e32 v2, 26, v2
	v_add_u32_e32 v2, v1, v2
	v_lshlrev_b32_e32 v3, 3, v8
	v_ashrrev_i32_e32 v9, 6, v2
	v_and_b32_e32 v3, -16, v3
	v_add_u32_e32 v3, v9, v3
	v_and_b32_e32 v4, 3, v9
	s_mov_b32 s0, 0xfffe0
	v_lshrrev_b32_e32 v5, 2, v3
	v_lshlrev_b32_e32 v6, 1, v3
	v_and_b32_e32 v2, 0xc0, v2
	v_and_or_b32 v4, v3, s0, v4
	v_and_b32_e32 v5, 4, v5
	v_and_b32_e32 v6, 24, v6
	v_sub_u32_e32 v1, v1, v2
	v_mov_b32_e32 v2, 1
	v_or3_b32 v4, v4, v5, v6
	v_lshlrev_b32_e32 v5, 5, v8
	v_ashrrev_i16_sdwa v1, v2, sext(v1) dst_sel:DWORD dst_unused:UNUSED_PAD src0_sel:DWORD src1_sel:BYTE_0
	v_and_b32_e32 v5, 32, v5
	v_bfe_i32 v10, v1, 0, 16
	v_add_lshl_u32 v1, v5, v10, 1
	v_lshl_add_u32 v128, v4, 12, v1
	v_lshl_add_u32 v130, v3, 12, v1
	v_bfe_i32 v1, v14, 27, 1
	v_lshrrev_b32_e32 v1, 22, v1
	v_add_u32_e32 v1, v0, v1
	v_and_b32_e32 v1, 0xfffffc00, v1
	v_sub_u32_e32 v0, v0, v1
	v_lshrrev_b32_e32 v1, 4, v0
	v_ashrrev_i32_e32 v3, 31, v14
	v_bitop3_b32 v0, v1, v0, 32 bitop3:0x6c
	v_lshrrev_b32_e32 v3, 26, v3
	v_ashrrev_i32_e32 v1, 31, v0
	v_add_u32_e32 v3, v14, v3
	v_lshrrev_b32_e32 v1, 26, v1
	v_ashrrev_i32_e32 v12, 6, v3
	v_add_u32_e32 v1, v0, v1
	v_lshlrev_b32_e32 v3, 3, v12
	v_ashrrev_i32_e32 v11, 6, v1
	v_and_b32_e32 v3, -16, v3
	v_add_u32_e32 v3, v11, v3
	v_and_b32_e32 v4, 3, v11
	v_and_or_b32 v4, v3, s0, v4
	s_lshr_b32 s0, s80, 29
	s_add_i32 s0, s95, s0
	s_ashr_i32 s6, s1, 6
	s_ashr_i32 s2, s0, 3
	s_and_b32 s0, s0, -8
	s_ashr_i32 s7, s1, 8
	s_lshl_b32 s25, s6, 10
	s_sub_i32 s0, s95, s0
	s_cmp_lt_i32 s0, 0
	s_movk_i32 s33, 0xb1
	s_cselect_b32 s3, s33, 0xb0
	s_mul_i32 s0, s0, s3
	s_add_i32 s0, s0, s2
	s_mul_hi_i32 s2, s0, 0x2e8ba2e9
	s_lshr_b32 s3, s2, 31
	s_ashr_i32 s2, s2, 6
	s_add_i32 s2, s2, s3
	s_lshl_b32 s3, s2, 3
	s_mulk_i32 s2, 0x160
	s_sub_i32 s2, s0, s2
	s_sext_i32_i16 s0, s2
	s_bfe_u32 s0, s0, 0x3001c
	s_add_i32 s4, s2, s0
	s_sext_i32_i16 s0, s4
	s_and_b32 s4, s4, 0xfff8
	s_sub_i32 s2, s2, s4
	s_sext_i32_i16 s2, s2
	v_lshrrev_b32_e32 v5, 2, v3
	v_lshlrev_b32_e32 v6, 1, v3
	v_and_b32_e32 v1, 0xc0, v1
	s_lshr_b32 s0, s0, 3
	s_add_i32 s2, s3, s2
	v_and_b32_e32 v5, 4, v5
	v_and_b32_e32 v6, 24, v6
	v_sub_u32_e32 v0, v0, v1
	s_ashr_i32 s3, s2, 31
	s_bfe_i64 s[8:9], s[0:1], 0x100000
	v_or3_b32 v4, v4, v5, v6
	v_lshlrev_b32_e32 v5, 5, v12
	v_ashrrev_i16_sdwa v0, v2, sext(v0) dst_sel:DWORD dst_unused:UNUSED_PAD src0_sel:DWORD src1_sel:BYTE_0
	s_lshl_b64 s[4:5], s[2:3], 20
	s_lshl_b64 s[8:9], s[8:9], 20
	v_and_b32_e32 v5, 32, v5
	v_bfe_i32 v13, v0, 0, 16
	s_add_u32 s28, s40, s8
	v_add_lshl_u32 v0, v5, v13, 1
	s_addc_u32 s29, s41, s9
	s_add_i32 s35, s25, 0
	v_lshl_add_u32 v132, v4, 12, v0
	v_and_b32_e32 v238, 15, v14
	v_lshl_or_b32 v238, s7, 6, v238
	v_lshl_add_u32 v238, s2, 8, v238
	v_lshlrev_b32_e32 v238, 2, v238
	global_load_dword v230, v238, s[78:79]
	global_load_dword v231, v238, s[78:79] offset:64
	global_load_dword v232, v238, s[78:79] offset:128
	global_load_dword v233, v238, s[78:79] offset:192
	global_load_dword v234, v238, s[78:79] offset:512
	global_load_dword v235, v238, s[78:79] offset:576
	global_load_dword v236, v238, s[78:79] offset:640
	global_load_dword v237, v238, s[78:79] offset:704
	s_add_i32 m0, s35, 0x10000
	v_lshl_add_u32 v134, v3, 12, v0
	global_load_lds_dwordx4 v132, s[28:29]
	s_add_i32 m0, s35, 0x12000
	s_add_u32 s8, s28, 0x80000
	global_load_lds_dwordx4 v128, s[28:29]
	s_addc_u32 s9, s29, 0
	s_add_i32 m0, s35, 0x14000
	v_mov_b32_e32 v133, 0
	global_load_lds_dwordx4 v132, s[8:9]
	s_add_i32 m0, s35, 0x16000
	s_add_u32 s26, s18, s4
	s_addc_u32 s27, s19, s5
	s_add_i32 s36, s35, 0x2000
	global_load_lds_dwordx4 v128, s[8:9]
	s_mov_b32 m0, s35
	s_add_u32 s4, s26, 0x80000
	global_load_lds_dwordx4 v134, s[26:27]
	s_mov_b32 m0, s36
	s_addc_u32 s5, s27, 0
	s_add_i32 s37, s35, 0x4000
	global_load_lds_dwordx4 v130, s[26:27]
	s_mov_b32 m0, s37
	s_add_i32 s38, s35, 0x6000
	global_load_lds_dwordx4 v134, s[4:5]
	s_mov_b32 m0, s38
	v_mov_b32_e32 v129, v133
	global_load_lds_dwordx4 v130, s[4:5]
	v_mov_b32_e32 v135, v133
	v_mov_b32_e32 v131, v133
	s_cmp_eq_u32 s7, 1
	s_mov_b32 s39, 0
	v_lshl_add_u64 v[6:7], s[28:29], 0, v[132:133]
	v_lshl_add_u64 v[4:5], s[28:29], 0, v[128:129]
	v_lshl_add_u64 v[0:1], s[26:27], 0, v[134:135]
	s_cselect_b64 s[4:5], -1, 0
	s_cmp_lg_u32 s7, 1
	v_lshl_add_u64 v[2:3], s[26:27], 0, v[130:131]
	s_cbranch_scc1 .LBB0_159
	s_barrier

.LBB0_168:
	s_waitcnt vmcnt(8)
	v_fmamk_f32 v158, v230, 0x3a000000, v156
	v_fmamk_f32 v159, v231, 0x3a000000, v156
	v_fmamk_f32 v160, v232, 0x3a000000, v156
	v_fmamk_f32 v161, v233, 0x3a000000, v156
	v_fmamk_f32 v162, v234, 0x3a000000, v156
	v_fmamk_f32 v163, v235, 0x3a000000, v156
	v_fmamk_f32 v164, v236, 0x3a000000, v156
	v_fmamk_f32 v165, v237, 0x3a000000, v156
	v_rsq_f32_e32 v158, v158
	v_rsq_f32_e32 v159, v159
	v_rsq_f32_e32 v160, v160
	v_rsq_f32_e32 v161, v161
	v_rsq_f32_e32 v162, v162
	v_rsq_f32_e32 v163, v163
	v_rsq_f32_e32 v164, v164
	v_rsq_f32_e32 v165, v165
	v_lshl_add_u32 v144, s2, 8, v150
	v_lshl_or_b32 v148, s3, 7, v152
	v_mul_u32_u24_e32 v145, 0x2c00, v144
	v_lshl_add_u32 v180, v148, 1, v145
	v_add_u32_e32 v181, 0x2c000, v180
	v_add_u32_e32 v182, 0x58000, v180
	v_add_u32_e32 v183, 0x84000, v180
	v_add_u32_e32 v184, 0x160000, v180
	v_add_u32_e32 v185, 0x18c000, v180
	v_add_u32_e32 v186, 0x1b8000, v180
	v_add_u32_e32 v187, 0x1e4000, v180
	s_and_b64 vcc, exec, s[0:1]
	s_cselect_b32 s2, s12, s2
	v_lshl_add_u32 v144, s2, 8, v150
	v_lshlrev_b32_e32 v144, 2, v144
	global_load_dword v230, v144, s[78:79]
	global_load_dword v231, v144, s[78:79] offset:64
	global_load_dword v232, v144, s[78:79] offset:128
	global_load_dword v233, v144, s[78:79] offset:192
	global_load_dword v234, v144, s[78:79] offset:512
	global_load_dword v235, v144, s[78:79] offset:576
	global_load_dword v236, v144, s[78:79] offset:640
	global_load_dword v237, v144, s[78:79] offset:704
	v_mul_f32_e32 v124, v124, v158
	v_mul_f32_e32 v125, v125, v158
	v_mul_f32_e32 v126, v126, v158
	v_mul_f32_e32 v127, v127, v158
	v_mul_f32_e32 v116, v116, v158
	v_mul_f32_e32 v117, v117, v158
	v_mul_f32_e32 v118, v118, v158
	v_mul_f32_e32 v119, v119, v158
	v_mul_f32_e32 v166, 0xbfb8aa3b, v124
	v_mul_f32_e32 v167, 0xbfb8aa3b, v125
	v_mul_f32_e32 v168, 0xbfb8aa3b, v126
	v_mul_f32_e32 v169, 0xbfb8aa3b, v127
	v_mul_f32_e32 v170, 0xbfb8aa3b, v116
	v_mul_f32_e32 v171, 0xbfb8aa3b, v117
	v_mul_f32_e32 v172, 0xbfb8aa3b, v118
	v_mul_f32_e32 v173, 0xbfb8aa3b, v119
	v_exp_f32_e32 v166, v166
	v_mul_f32_e32 v120, v120, v158
	v_exp_f32_e32 v167, v167
	v_mul_f32_e32 v121, v121, v158
	v_exp_f32_e32 v168, v168
	v_mul_f32_e32 v122, v122, v158
	v_exp_f32_e32 v169, v169
	v_mul_f32_e32 v123, v123, v158
	v_exp_f32_e32 v170, v170
	v_mul_f32_e32 v112, v112, v158
	v_exp_f32_e32 v171, v171
	v_mul_f32_e32 v113, v113, v158
	v_exp_f32_e32 v172, v172
	v_mul_f32_e32 v114, v114, v158
	v_exp_f32_e32 v173, v173
	v_mul_f32_e32 v115, v115, v158
	v_add_f32_e32 v166, 1.0, v166
	v_add_f32_e32 v167, 1.0, v167
	v_add_f32_e32 v168, 1.0, v168
	v_add_f32_e32 v169, 1.0, v169
	v_add_f32_e32 v170, 1.0, v170
	v_add_f32_e32 v171, 1.0, v171
	v_add_f32_e32 v172, 1.0, v172
	v_add_f32_e32 v173, 1.0, v173
	v_rcp_f32_e32 v166, v166
	v_rcp_f32_e32 v167, v167
	v_rcp_f32_e32 v168, v168
	v_rcp_f32_e32 v169, v169
	v_rcp_f32_e32 v170, v170
	v_rcp_f32_e32 v171, v171
	v_rcp_f32_e32 v172, v172
	v_rcp_f32_e32 v173, v173
	v_mul_f32_e32 v124, v124, v166
	v_mul_f32_e32 v125, v125, v167
	v_mul_f32_e32 v126, v126, v168
	v_mul_f32_e32 v127, v127, v169
	v_mul_f32_e32 v116, v116, v170
	v_mul_f32_e32 v117, v117, v171
	v_mul_f32_e32 v118, v118, v172
	v_mul_f32_e32 v119, v119, v173
	v_mul_f32_e32 v120, v120, v124
	v_mul_f32_e32 v121, v121, v125
	v_mul_f32_e32 v122, v122, v126
	v_mul_f32_e32 v123, v123, v127
	v_mul_f32_e32 v112, v112, v116
	v_mul_f32_e32 v113, v113, v117
	v_mul_f32_e32 v114, v114, v118
	v_mul_f32_e32 v115, v115, v119
	v_cvt_pk_bf16_f32 v120, v120, v121
	v_cvt_pk_bf16_f32 v121, v122, v123
	v_cvt_pk_bf16_f32 v122, v112, v113
	v_cvt_pk_bf16_f32 v123, v114, v115
	global_store_dwordx4 v180, v[120:123], s[16:17]
	v_mul_f32_e32 v108, v108, v159
	v_mul_f32_e32 v109, v109, v159
	v_mul_f32_e32 v110, v110, v159
	v_mul_f32_e32 v111, v111, v159
	v_mul_f32_e32 v100, v100, v159
	v_mul_f32_e32 v101, v101, v159
	v_mul_f32_e32 v102, v102, v159
	v_mul_f32_e32 v103, v103, v159
	v_mul_f32_e32 v166, 0xbfb8aa3b, v108
	v_mul_f32_e32 v167, 0xbfb8aa3b, v109
	v_mul_f32_e32 v168, 0xbfb8aa3b, v110
	v_mul_f32_e32 v169, 0xbfb8aa3b, v111
	v_mul_f32_e32 v170, 0xbfb8aa3b, v100
	v_mul_f32_e32 v171, 0xbfb8aa3b, v101
	v_mul_f32_e32 v172, 0xbfb8aa3b, v102
	v_mul_f32_e32 v173, 0xbfb8aa3b, v103
	v_exp_f32_e32 v166, v166
	v_mul_f32_e32 v104, v104, v159
	v_exp_f32_e32 v167, v167
	v_mul_f32_e32 v105, v105, v159
	v_exp_f32_e32 v168, v168
	v_mul_f32_e32 v106, v106, v159
	v_exp_f32_e32 v169, v169
	v_mul_f32_e32 v107, v107, v159
	v_exp_f32_e32 v170, v170
	v_mul_f32_e32 v96, v96, v159
	v_exp_f32_e32 v171, v171
	v_mul_f32_e32 v97, v97, v159
	v_exp_f32_e32 v172, v172
	v_mul_f32_e32 v98, v98, v159
	v_exp_f32_e32 v173, v173
	v_mul_f32_e32 v99, v99, v159
	v_add_f32_e32 v166, 1.0, v166
	v_add_f32_e32 v167, 1.0, v167
	v_add_f32_e32 v168, 1.0, v168
	v_add_f32_e32 v169, 1.0, v169
	v_add_f32_e32 v170, 1.0, v170
	v_add_f32_e32 v171, 1.0, v171
	v_add_f32_e32 v172, 1.0, v172
	v_add_f32_e32 v173, 1.0, v173
	v_rcp_f32_e32 v166, v166
	v_rcp_f32_e32 v167, v167
	v_rcp_f32_e32 v168, v168
	v_rcp_f32_e32 v169, v169
	v_rcp_f32_e32 v170, v170
	v_rcp_f32_e32 v171, v171
	v_rcp_f32_e32 v172, v172
	v_rcp_f32_e32 v173, v173
	v_mul_f32_e32 v108, v108, v166
	v_mul_f32_e32 v109, v109, v167
	v_mul_f32_e32 v110, v110, v168
	v_mul_f32_e32 v111, v111, v169
	v_mul_f32_e32 v100, v100, v170
	v_mul_f32_e32 v101, v101, v171
	v_mul_f32_e32 v102, v102, v172
	v_mul_f32_e32 v103, v103, v173
	v_mul_f32_e32 v104, v104, v108
	v_mul_f32_e32 v105, v105, v109
	v_mul_f32_e32 v106, v106, v110
	v_mul_f32_e32 v107, v107, v111
	v_mul_f32_e32 v96, v96, v100
	v_mul_f32_e32 v97, v97, v101
	v_mul_f32_e32 v98, v98, v102
	v_mul_f32_e32 v99, v99, v103
	v_cvt_pk_bf16_f32 v104, v104, v105
	v_cvt_pk_bf16_f32 v105, v106, v107
	v_cvt_pk_bf16_f32 v106, v96, v97
	v_cvt_pk_bf16_f32 v107, v98, v99
	global_store_dwordx4 v181, v[104:107], s[16:17]
	v_mul_f32_e32 v92, v92, v160
	v_mul_f32_e32 v93, v93, v160
	v_mul_f32_e32 v94, v94, v160
	v_mul_f32_e32 v95, v95, v160
	v_mul_f32_e32 v84, v84, v160
	v_mul_f32_e32 v85, v85, v160
	v_mul_f32_e32 v86, v86, v160
	v_mul_f32_e32 v87, v87, v160
	v_mul_f32_e32 v166, 0xbfb8aa3b, v92
	v_mul_f32_e32 v167, 0xbfb8aa3b, v93
	v_mul_f32_e32 v168, 0xbfb8aa3b, v94
	v_mul_f32_e32 v169, 0xbfb8aa3b, v95
	v_mul_f32_e32 v170, 0xbfb8aa3b, v84
	v_mul_f32_e32 v171, 0xbfb8aa3b, v85
	v_mul_f32_e32 v172, 0xbfb8aa3b, v86
	v_mul_f32_e32 v173, 0xbfb8aa3b, v87
	v_exp_f32_e32 v166, v166
	v_mul_f32_e32 v88, v88, v160
	v_exp_f32_e32 v167, v167
	v_mul_f32_e32 v89, v89, v160
	v_exp_f32_e32 v168, v168
	v_mul_f32_e32 v90, v90, v160
	v_exp_f32_e32 v169, v169
	v_mul_f32_e32 v91, v91, v160
	v_exp_f32_e32 v170, v170
	v_mul_f32_e32 v80, v80, v160
	v_exp_f32_e32 v171, v171
	v_mul_f32_e32 v81, v81, v160
	v_exp_f32_e32 v172, v172
	v_mul_f32_e32 v82, v82, v160
	v_exp_f32_e32 v173, v173
	v_mul_f32_e32 v83, v83, v160
	v_add_f32_e32 v166, 1.0, v166
	v_add_f32_e32 v167, 1.0, v167
	v_add_f32_e32 v168, 1.0, v168
	v_add_f32_e32 v169, 1.0, v169
	v_add_f32_e32 v170, 1.0, v170
	v_add_f32_e32 v171, 1.0, v171
	v_add_f32_e32 v172, 1.0, v172
	v_add_f32_e32 v173, 1.0, v173
	v_rcp_f32_e32 v166, v166
	v_rcp_f32_e32 v167, v167
	v_rcp_f32_e32 v168, v168
	v_rcp_f32_e32 v169, v169
	v_rcp_f32_e32 v170, v170
	v_rcp_f32_e32 v171, v171
	v_rcp_f32_e32 v172, v172
	v_rcp_f32_e32 v173, v173
	v_mul_f32_e32 v92, v92, v166
	v_mul_f32_e32 v93, v93, v167
	v_mul_f32_e32 v94, v94, v168
	v_mul_f32_e32 v95, v95, v169
	v_mul_f32_e32 v84, v84, v170
	v_mul_f32_e32 v85, v85, v171
	v_mul_f32_e32 v86, v86, v172
	v_mul_f32_e32 v87, v87, v173
	v_mul_f32_e32 v88, v88, v92
	v_mul_f32_e32 v89, v89, v93
	v_mul_f32_e32 v90, v90, v94
	v_mul_f32_e32 v91, v91, v95
	v_mul_f32_e32 v80, v80, v84
	v_mul_f32_e32 v81, v81, v85
	v_mul_f32_e32 v82, v82, v86
	v_mul_f32_e32 v83, v83, v87
	v_cvt_pk_bf16_f32 v88, v88, v89
	v_cvt_pk_bf16_f32 v89, v90, v91
	v_cvt_pk_bf16_f32 v90, v80, v81
	v_cvt_pk_bf16_f32 v91, v82, v83
	global_store_dwordx4 v182, v[88:91], s[16:17]
	v_mul_f32_e32 v76, v76, v161
	v_mul_f32_e32 v77, v77, v161
	v_mul_f32_e32 v78, v78, v161
	v_mul_f32_e32 v79, v79, v161
	v_mul_f32_e32 v68, v68, v161
	v_mul_f32_e32 v69, v69, v161
	v_mul_f32_e32 v70, v70, v161
	v_mul_f32_e32 v71, v71, v161
	v_mul_f32_e32 v166, 0xbfb8aa3b, v76
	v_mul_f32_e32 v167, 0xbfb8aa3b, v77
	v_mul_f32_e32 v168, 0xbfb8aa3b, v78
	v_mul_f32_e32 v169, 0xbfb8aa3b, v79
	v_mul_f32_e32 v170, 0xbfb8aa3b, v68
	v_mul_f32_e32 v171, 0xbfb8aa3b, v69
	v_mul_f32_e32 v172, 0xbfb8aa3b, v70
	v_mul_f32_e32 v173, 0xbfb8aa3b, v71
	v_exp_f32_e32 v166, v166
	v_mul_f32_e32 v72, v72, v161
	v_exp_f32_e32 v167, v167
	v_mul_f32_e32 v73, v73, v161
	v_exp_f32_e32 v168, v168
	v_mul_f32_e32 v74, v74, v161
	v_exp_f32_e32 v169, v169
	v_mul_f32_e32 v75, v75, v161
	v_exp_f32_e32 v170, v170
	v_mul_f32_e32 v64, v64, v161
	v_exp_f32_e32 v171, v171
	v_mul_f32_e32 v65, v65, v161
	v_exp_f32_e32 v172, v172
	v_mul_f32_e32 v66, v66, v161
	v_exp_f32_e32 v173, v173
	v_mul_f32_e32 v67, v67, v161
	v_add_f32_e32 v166, 1.0, v166
	v_add_f32_e32 v167, 1.0, v167
	v_add_f32_e32 v168, 1.0, v168
	v_add_f32_e32 v169, 1.0, v169
	v_add_f32_e32 v170, 1.0, v170
	v_add_f32_e32 v171, 1.0, v171
	v_add_f32_e32 v172, 1.0, v172
	v_add_f32_e32 v173, 1.0, v173
	v_rcp_f32_e32 v166, v166
	v_rcp_f32_e32 v167, v167
	v_rcp_f32_e32 v168, v168
	v_rcp_f32_e32 v169, v169
	v_rcp_f32_e32 v170, v170
	v_rcp_f32_e32 v171, v171
	v_rcp_f32_e32 v172, v172
	v_rcp_f32_e32 v173, v173
	v_mul_f32_e32 v76, v76, v166
	v_mul_f32_e32 v77, v77, v167
	v_mul_f32_e32 v78, v78, v168
	v_mul_f32_e32 v79, v79, v169
	v_mul_f32_e32 v68, v68, v170
	v_mul_f32_e32 v69, v69, v171
	v_mul_f32_e32 v70, v70, v172
	v_mul_f32_e32 v71, v71, v173
	v_mul_f32_e32 v72, v72, v76
	v_mul_f32_e32 v73, v73, v77
	v_mul_f32_e32 v74, v74, v78
	v_mul_f32_e32 v75, v75, v79
	v_mul_f32_e32 v64, v64, v68
	v_mul_f32_e32 v65, v65, v69
	v_mul_f32_e32 v66, v66, v70
	v_mul_f32_e32 v67, v67, v71
	v_cvt_pk_bf16_f32 v72, v72, v73
	v_cvt_pk_bf16_f32 v73, v74, v75
	v_cvt_pk_bf16_f32 v74, v64, v65
	v_cvt_pk_bf16_f32 v75, v66, v67
	global_store_dwordx4 v183, v[72:75], s[16:17]
	v_mul_f32_e32 v60, v60, v162
	v_mul_f32_e32 v61, v61, v162
	v_mul_f32_e32 v62, v62, v162
	v_mul_f32_e32 v63, v63, v162
	v_mul_f32_e32 v52, v52, v162
	v_mul_f32_e32 v53, v53, v162
	v_mul_f32_e32 v54, v54, v162
	v_mul_f32_e32 v55, v55, v162
	v_mul_f32_e32 v166, 0xbfb8aa3b, v60
	v_mul_f32_e32 v167, 0xbfb8aa3b, v61
	v_mul_f32_e32 v168, 0xbfb8aa3b, v62
	v_mul_f32_e32 v169, 0xbfb8aa3b, v63
	v_mul_f32_e32 v170, 0xbfb8aa3b, v52
	v_mul_f32_e32 v171, 0xbfb8aa3b, v53
	v_mul_f32_e32 v172, 0xbfb8aa3b, v54
	v_mul_f32_e32 v173, 0xbfb8aa3b, v55
	v_exp_f32_e32 v166, v166
	v_mul_f32_e32 v56, v56, v162
	v_exp_f32_e32 v167, v167
	v_mul_f32_e32 v57, v57, v162
	v_exp_f32_e32 v168, v168
	v_mul_f32_e32 v58, v58, v162
	v_exp_f32_e32 v169, v169
	v_mul_f32_e32 v59, v59, v162
	v_exp_f32_e32 v170, v170
	v_mul_f32_e32 v48, v48, v162
	v_exp_f32_e32 v171, v171
	v_mul_f32_e32 v49, v49, v162
	v_exp_f32_e32 v172, v172
	v_mul_f32_e32 v50, v50, v162
	v_exp_f32_e32 v173, v173
	v_mul_f32_e32 v51, v51, v162
	v_add_f32_e32 v166, 1.0, v166
	v_add_f32_e32 v167, 1.0, v167
	v_add_f32_e32 v168, 1.0, v168
	v_add_f32_e32 v169, 1.0, v169
	v_add_f32_e32 v170, 1.0, v170
	v_add_f32_e32 v171, 1.0, v171
	v_add_f32_e32 v172, 1.0, v172
	v_add_f32_e32 v173, 1.0, v173
	v_rcp_f32_e32 v166, v166
	v_rcp_f32_e32 v167, v167
	v_rcp_f32_e32 v168, v168
	v_rcp_f32_e32 v169, v169
	v_rcp_f32_e32 v170, v170
	v_rcp_f32_e32 v171, v171
	v_rcp_f32_e32 v172, v172
	v_rcp_f32_e32 v173, v173
	v_mul_f32_e32 v60, v60, v166
	v_mul_f32_e32 v61, v61, v167
	v_mul_f32_e32 v62, v62, v168
	v_mul_f32_e32 v63, v63, v169
	v_mul_f32_e32 v52, v52, v170
	v_mul_f32_e32 v53, v53, v171
	v_mul_f32_e32 v54, v54, v172
	v_mul_f32_e32 v55, v55, v173
	v_mul_f32_e32 v56, v56, v60
	v_mul_f32_e32 v57, v57, v61
	v_mul_f32_e32 v58, v58, v62
	v_mul_f32_e32 v59, v59, v63
	v_mul_f32_e32 v48, v48, v52
	v_mul_f32_e32 v49, v49, v53
	v_mul_f32_e32 v50, v50, v54
	v_mul_f32_e32 v51, v51, v55
	v_cvt_pk_bf16_f32 v56, v56, v57
	v_cvt_pk_bf16_f32 v57, v58, v59
	v_cvt_pk_bf16_f32 v58, v48, v49
	v_cvt_pk_bf16_f32 v59, v50, v51
	global_store_dwordx4 v184, v[56:59], s[16:17]
	v_mul_f32_e32 v44, v44, v163
	v_mul_f32_e32 v45, v45, v163
	v_mul_f32_e32 v46, v46, v163
	v_mul_f32_e32 v47, v47, v163
	v_mul_f32_e32 v36, v36, v163
	v_mul_f32_e32 v37, v37, v163
	v_mul_f32_e32 v38, v38, v163
	v_mul_f32_e32 v39, v39, v163
	v_mul_f32_e32 v166, 0xbfb8aa3b, v44
	v_mul_f32_e32 v167, 0xbfb8aa3b, v45
	v_mul_f32_e32 v168, 0xbfb8aa3b, v46
	v_mul_f32_e32 v169, 0xbfb8aa3b, v47
	v_mul_f32_e32 v170, 0xbfb8aa3b, v36
	v_mul_f32_e32 v171, 0xbfb8aa3b, v37
	v_mul_f32_e32 v172, 0xbfb8aa3b, v38
	v_mul_f32_e32 v173, 0xbfb8aa3b, v39
	v_exp_f32_e32 v166, v166
	v_mul_f32_e32 v40, v40, v163
	v_exp_f32_e32 v167, v167
	v_mul_f32_e32 v41, v41, v163
	v_exp_f32_e32 v168, v168
	v_mul_f32_e32 v42, v42, v163
	v_exp_f32_e32 v169, v169
	v_mul_f32_e32 v43, v43, v163
	v_exp_f32_e32 v170, v170
	v_mul_f32_e32 v32, v32, v163
	v_exp_f32_e32 v171, v171
	v_mul_f32_e32 v33, v33, v163
	v_exp_f32_e32 v172, v172
	v_mul_f32_e32 v34, v34, v163
	v_exp_f32_e32 v173, v173
	v_mul_f32_e32 v35, v35, v163
	v_add_f32_e32 v166, 1.0, v166
	v_add_f32_e32 v167, 1.0, v167
	v_add_f32_e32 v168, 1.0, v168
	v_add_f32_e32 v169, 1.0, v169
	v_add_f32_e32 v170, 1.0, v170
	v_add_f32_e32 v171, 1.0, v171
	v_add_f32_e32 v172, 1.0, v172
	v_add_f32_e32 v173, 1.0, v173
	v_rcp_f32_e32 v166, v166
	v_rcp_f32_e32 v167, v167
	v_rcp_f32_e32 v168, v168
	v_rcp_f32_e32 v169, v169
	v_rcp_f32_e32 v170, v170
	v_rcp_f32_e32 v171, v171
	v_rcp_f32_e32 v172, v172
	v_rcp_f32_e32 v173, v173
	v_mul_f32_e32 v44, v44, v166
	v_mul_f32_e32 v45, v45, v167
	v_mul_f32_e32 v46, v46, v168
	v_mul_f32_e32 v47, v47, v169
	v_mul_f32_e32 v36, v36, v170
	v_mul_f32_e32 v37, v37, v171
	v_mul_f32_e32 v38, v38, v172
	v_mul_f32_e32 v39, v39, v173
	v_mul_f32_e32 v40, v40, v44
	v_mul_f32_e32 v41, v41, v45
	v_mul_f32_e32 v42, v42, v46
	v_mul_f32_e32 v43, v43, v47
	v_mul_f32_e32 v32, v32, v36
	v_mul_f32_e32 v33, v33, v37
	v_mul_f32_e32 v34, v34, v38
	v_mul_f32_e32 v35, v35, v39
	v_cvt_pk_bf16_f32 v40, v40, v41
	v_cvt_pk_bf16_f32 v41, v42, v43
	v_cvt_pk_bf16_f32 v42, v32, v33
	v_cvt_pk_bf16_f32 v43, v34, v35
	global_store_dwordx4 v185, v[40:43], s[16:17]
	v_mul_f32_e32 v28, v28, v164
	v_mul_f32_e32 v29, v29, v164
	v_mul_f32_e32 v30, v30, v164
	v_mul_f32_e32 v31, v31, v164
	v_mul_f32_e32 v20, v20, v164
	v_mul_f32_e32 v21, v21, v164
	v_mul_f32_e32 v22, v22, v164
	v_mul_f32_e32 v23, v23, v164
	v_mul_f32_e32 v166, 0xbfb8aa3b, v28
	v_mul_f32_e32 v167, 0xbfb8aa3b, v29
	v_mul_f32_e32 v168, 0xbfb8aa3b, v30
	v_mul_f32_e32 v169, 0xbfb8aa3b, v31
	v_mul_f32_e32 v170, 0xbfb8aa3b, v20
	v_mul_f32_e32 v171, 0xbfb8aa3b, v21
	v_mul_f32_e32 v172, 0xbfb8aa3b, v22
	v_mul_f32_e32 v173, 0xbfb8aa3b, v23
	v_exp_f32_e32 v166, v166
	v_mul_f32_e32 v24, v24, v164
	v_exp_f32_e32 v167, v167
	v_mul_f32_e32 v25, v25, v164
	v_exp_f32_e32 v168, v168
	v_mul_f32_e32 v26, v26, v164
	v_exp_f32_e32 v169, v169
	v_mul_f32_e32 v27, v27, v164
	v_exp_f32_e32 v170, v170
	v_mul_f32_e32 v16, v16, v164
	v_exp_f32_e32 v171, v171
	v_mul_f32_e32 v17, v17, v164
	v_exp_f32_e32 v172, v172
	v_mul_f32_e32 v18, v18, v164
	v_exp_f32_e32 v173, v173
	v_mul_f32_e32 v19, v19, v164
	v_add_f32_e32 v166, 1.0, v166
	v_add_f32_e32 v167, 1.0, v167
	v_add_f32_e32 v168, 1.0, v168
	v_add_f32_e32 v169, 1.0, v169
	v_add_f32_e32 v170, 1.0, v170
	v_add_f32_e32 v171, 1.0, v171
	v_add_f32_e32 v172, 1.0, v172
	v_add_f32_e32 v173, 1.0, v173
	v_rcp_f32_e32 v166, v166
	v_rcp_f32_e32 v167, v167
	v_rcp_f32_e32 v168, v168
	v_rcp_f32_e32 v169, v169
	v_rcp_f32_e32 v170, v170
	v_rcp_f32_e32 v171, v171
	v_rcp_f32_e32 v172, v172
	v_rcp_f32_e32 v173, v173
	v_mul_f32_e32 v28, v28, v166
	v_mul_f32_e32 v29, v29, v167
	v_mul_f32_e32 v30, v30, v168
	v_mul_f32_e32 v31, v31, v169
	v_mul_f32_e32 v20, v20, v170
	v_mul_f32_e32 v21, v21, v171
	v_mul_f32_e32 v22, v22, v172
	v_mul_f32_e32 v23, v23, v173
	v_mul_f32_e32 v24, v24, v28
	v_mul_f32_e32 v25, v25, v29
	v_mul_f32_e32 v26, v26, v30
	v_mul_f32_e32 v27, v27, v31
	v_mul_f32_e32 v16, v16, v20
	v_mul_f32_e32 v17, v17, v21
	v_mul_f32_e32 v18, v18, v22
	v_mul_f32_e32 v19, v19, v23
	v_cvt_pk_bf16_f32 v24, v24, v25
	v_cvt_pk_bf16_f32 v25, v26, v27
	v_cvt_pk_bf16_f32 v26, v16, v17
	v_cvt_pk_bf16_f32 v27, v18, v19
	global_store_dwordx4 v186, v[24:27], s[16:17]
	v_mul_f32_e32 v12, v12, v165
	v_mul_f32_e32 v13, v13, v165
	v_mul_f32_e32 v14, v14, v165
	v_mul_f32_e32 v15, v15, v165
	v_mul_f32_e32 v4, v4, v165
	v_mul_f32_e32 v5, v5, v165
	v_mul_f32_e32 v6, v6, v165
	v_mul_f32_e32 v7, v7, v165
	v_mul_f32_e32 v166, 0xbfb8aa3b, v12
	v_mul_f32_e32 v167, 0xbfb8aa3b, v13
	v_mul_f32_e32 v168, 0xbfb8aa3b, v14
	v_mul_f32_e32 v169, 0xbfb8aa3b, v15
	v_mul_f32_e32 v170, 0xbfb8aa3b, v4
	v_mul_f32_e32 v171, 0xbfb8aa3b, v5
	v_mul_f32_e32 v172, 0xbfb8aa3b, v6
	v_mul_f32_e32 v173, 0xbfb8aa3b, v7
	v_exp_f32_e32 v166, v166
	v_mul_f32_e32 v8, v8, v165
	v_exp_f32_e32 v167, v167
	v_mul_f32_e32 v9, v9, v165
	v_exp_f32_e32 v168, v168
	v_mul_f32_e32 v10, v10, v165
	v_exp_f32_e32 v169, v169
	v_mul_f32_e32 v11, v11, v165
	v_exp_f32_e32 v170, v170
	v_mul_f32_e32 v0, v0, v165
	v_exp_f32_e32 v171, v171
	v_mul_f32_e32 v1, v1, v165
	v_exp_f32_e32 v172, v172
	v_mul_f32_e32 v2, v2, v165
	v_exp_f32_e32 v173, v173
	v_mul_f32_e32 v3, v3, v165
	v_add_f32_e32 v166, 1.0, v166
	v_add_f32_e32 v167, 1.0, v167
	v_add_f32_e32 v168, 1.0, v168
	v_add_f32_e32 v169, 1.0, v169
	v_add_f32_e32 v170, 1.0, v170
	v_add_f32_e32 v171, 1.0, v171
	v_add_f32_e32 v172, 1.0, v172
	v_add_f32_e32 v173, 1.0, v173
	v_rcp_f32_e32 v166, v166
	v_rcp_f32_e32 v167, v167
	v_rcp_f32_e32 v168, v168
	v_rcp_f32_e32 v169, v169
	v_rcp_f32_e32 v170, v170
	v_rcp_f32_e32 v171, v171
	v_rcp_f32_e32 v172, v172
	v_rcp_f32_e32 v173, v173
	v_mul_f32_e32 v12, v12, v166
	v_mul_f32_e32 v13, v13, v167
	v_mul_f32_e32 v14, v14, v168
	v_mul_f32_e32 v15, v15, v169
	v_mul_f32_e32 v4, v4, v170
	v_mul_f32_e32 v5, v5, v171
	v_mul_f32_e32 v6, v6, v172
	v_mul_f32_e32 v7, v7, v173
	v_mul_f32_e32 v8, v8, v12
	v_mul_f32_e32 v9, v9, v13
	v_mul_f32_e32 v10, v10, v14
	v_mul_f32_e32 v11, v11, v15
	v_mul_f32_e32 v0, v0, v4
	v_mul_f32_e32 v1, v1, v5
	v_mul_f32_e32 v2, v2, v6
	v_mul_f32_e32 v3, v3, v7
	v_cvt_pk_bf16_f32 v8, v8, v9
	v_cvt_pk_bf16_f32 v9, v10, v11
	v_cvt_pk_bf16_f32 v10, v0, v1
	v_cvt_pk_bf16_f32 v11, v2, v3
	s_andn2_b64 vcc, exec, s[0:1]
	s_mov_b64 s[2:3], -1
	global_store_dwordx4 v187, v[8:11], s[16:17]
	s_cbranch_vccnz .LBB0_161
	s_andn2_b64 vcc, exec, s[4:5]
	s_cbranch_vccnz .LBB0_160
	s_barrier
	s_branch .LBB0_160
